# up half-unit K-loops no longer stage or read the unused A half (12 instead of 16 LDS-DMA loads, 32 instead of 48 fragment reads per trip)
# baseline (speedup 1.0000x reference)
.Lup_half_peel:
	s_add_u32 s2, s10, 0xfffc0080
	s_addc_u32 s3, s11, -1
	ds_read_b128 v[48:51], v237
	ds_read_b128 v[52:55], v237 offset:1024
	ds_read_b128 v[104:107], v237 offset:2048
	ds_read_b128 v[108:111], v237 offset:3072
	s_cmp_eq_u32 s67, 12
	s_cselect_b32 s13, s1, s3
	s_cselect_b32 s12, s9, s2
	s_cselect_b32 s3, s14, s39
	s_cselect_b32 s2, s15, s37
	ds_read_b128 v[112:115], v238
	ds_read_b128 v[116:119], v238 offset:1024
	ds_read_b128 v[120:123], v238 offset:2048
	ds_read_b128 v[156:159], v238 offset:3072
	ds_read_b128 v[160:163], v238 offset:4096
	ds_read_b128 v[164:167], v238 offset:5120
	ds_read_b128 v[190:193], v238 offset:6144
	ds_read_b128 v[194:197], v238 offset:7168
	s_waitcnt lgkmcnt(8)
	s_barrier
	s_waitcnt lgkmcnt(0)
	v_mfma_f32_16x16x32_bf16 v[152:155], v[48:51], v[112:115], 0
	v_mfma_f32_16x16x32_bf16 v[68:71], v[104:107], v[112:115], 0
	v_mfma_f32_16x16x32_bf16 v[148:151], v[48:51], v[120:123], 0
	v_mfma_f32_16x16x32_bf16 v[64:67], v[104:107], v[120:123], 0
	v_mfma_f32_16x16x32_bf16 v[136:139], v[48:51], v[160:163], 0
	v_mfma_f32_16x16x32_bf16 v[44:47], v[104:107], v[160:163], 0
	v_mfma_f32_16x16x32_bf16 v[128:131], v[48:51], v[190:193], 0
	v_mfma_f32_16x16x32_bf16 v[40:43], v[104:107], v[190:193], 0
	v_mfma_f32_16x16x32_bf16 v[152:155], v[52:55], v[116:119], v[152:155]
	v_mfma_f32_16x16x32_bf16 v[68:71], v[108:111], v[116:119], v[68:71]
	v_mfma_f32_16x16x32_bf16 v[148:151], v[52:55], v[156:159], v[148:151]
	v_mfma_f32_16x16x32_bf16 v[64:67], v[108:111], v[156:159], v[64:67]
	v_mfma_f32_16x16x32_bf16 v[136:139], v[52:55], v[164:167], v[136:139]
	v_mfma_f32_16x16x32_bf16 v[44:47], v[108:111], v[164:167], v[44:47]
	v_mfma_f32_16x16x32_bf16 v[128:131], v[52:55], v[194:197], v[128:131]
	v_mfma_f32_16x16x32_bf16 v[40:43], v[108:111], v[194:197], v[40:43]
	s_barrier
	s_add_u32 s98, s2, 0x80
	s_addc_u32 s99, s3, 0
	s_add_i32 m0, s53, 0x10000
	ds_read_b128 v[198:201], v237 offset:16384
	ds_read_b128 v[202:205], v237 offset:17408
	ds_read_b128 v[206:209], v237 offset:18432
	global_load_lds_dwordx4 v168, s[2:3]
	s_add_i32 m0, s53, 0x12000
	ds_read_b128 v[210:213], v237 offset:19456
	global_load_lds_dwordx4 v184, s[2:3]
	s_barrier
	s_waitcnt lgkmcnt(0)
	v_mfma_f32_16x16x32_bf16 v[144:147], v[198:201], v[112:115], 0
	v_mfma_f32_16x16x32_bf16 v[60:63], v[206:209], v[112:115], 0
	v_mfma_f32_16x16x32_bf16 v[56:59], v[206:209], v[120:123], 0
	v_mfma_f32_16x16x32_bf16 v[36:39], v[206:209], v[160:163], 0
	v_mfma_f32_16x16x32_bf16 v[32:35], v[206:209], v[190:193], 0
	v_mfma_f32_16x16x32_bf16 v[144:147], v[202:205], v[116:119], v[144:147]
	v_mfma_f32_16x16x32_bf16 v[60:63], v[210:213], v[116:119], v[60:63]
	v_mfma_f32_16x16x32_bf16 v[112:115], v[198:201], v[120:123], 0
	v_mfma_f32_16x16x32_bf16 v[56:59], v[210:213], v[156:159], v[56:59]
	v_mfma_f32_16x16x32_bf16 v[116:119], v[198:201], v[160:163], 0
	v_mfma_f32_16x16x32_bf16 v[36:39], v[210:213], v[164:167], v[36:39]
	v_mfma_f32_16x16x32_bf16 v[120:123], v[198:201], v[190:193], 0
	v_mfma_f32_16x16x32_bf16 v[32:35], v[210:213], v[194:197], v[32:35]
	v_mfma_f32_16x16x32_bf16 v[112:115], v[202:205], v[156:159], v[112:115]
	v_mfma_f32_16x16x32_bf16 v[116:119], v[202:205], v[164:167], v[116:119]
	v_mfma_f32_16x16x32_bf16 v[120:123], v[202:205], v[194:197], v[120:123]
	s_mov_b32 m0, s54
	s_add_u32 s100, s12, 0x80
	s_addc_u32 s101, s13, 0
	s_barrier
	global_load_lds_dwordx4 v180, s[12:13]
	s_mov_b32 m0, s55
	s_nop 0
	global_load_lds_dwordx4 v182, s[12:13]
	s_barrier
	s_waitcnt lgkmcnt(0)
	s_barrier
	s_add_i32 m0, s53, 0x14000
	s_add_u32 s68, s2, 0x40000
	s_addc_u32 s69, s3, 0
	global_load_lds_dwordx4 v168, s[68:69]
	s_add_i32 m0, s53, 0x16000
	s_add_u32 s12, s12, 0x40000
	s_addc_u32 s13, s13, 0
	global_load_lds_dwordx4 v184, s[68:69]
	s_waitcnt vmcnt(6)
	s_barrier
	s_barrier
	ds_read_b128 v[76:79], v237 offset:32768
	ds_read_b128 v[92:95], v237 offset:33792
	ds_read_b128 v[104:107], v237 offset:34816
	ds_read_b128 v[108:111], v237 offset:35840
	ds_read_b128 v[124:127], v238 offset:32768
	ds_read_b128 v[132:135], v238 offset:33792
	ds_read_b128 v[156:159], v238 offset:34816
	ds_read_b128 v[160:163], v238 offset:35840
	ds_read_b128 v[164:167], v238 offset:36864
	ds_read_b128 v[190:193], v238 offset:37888
	ds_read_b128 v[194:197], v238 offset:38912
	ds_read_b128 v[198:201], v238 offset:39936
	s_waitcnt lgkmcnt(8)
	s_barrier
	s_waitcnt lgkmcnt(0)
	v_mfma_f32_16x16x32_bf16 v[140:143], v[76:79], v[124:127], v[152:155]
	v_mfma_f32_16x16x32_bf16 v[152:155], v[92:95], v[132:135], v[140:143]
	v_mfma_f32_16x16x32_bf16 v[68:71], v[104:107], v[124:127], v[68:71]
	v_mfma_f32_16x16x32_bf16 v[140:143], v[76:79], v[156:159], v[148:151]
	v_mfma_f32_16x16x32_bf16 v[64:67], v[104:107], v[156:159], v[64:67]
	v_mfma_f32_16x16x32_bf16 v[136:139], v[76:79], v[164:167], v[136:139]
	v_mfma_f32_16x16x32_bf16 v[44:47], v[104:107], v[164:167], v[44:47]
	v_mfma_f32_16x16x32_bf16 v[128:131], v[76:79], v[194:197], v[128:131]
	v_mfma_f32_16x16x32_bf16 v[40:43], v[104:107], v[194:197], v[40:43]
	v_mfma_f32_16x16x32_bf16 v[68:71], v[108:111], v[132:135], v[68:71]
	v_mfma_f32_16x16x32_bf16 v[148:151], v[92:95], v[160:163], v[140:143]
	v_mfma_f32_16x16x32_bf16 v[64:67], v[108:111], v[160:163], v[64:67]
	v_mfma_f32_16x16x32_bf16 v[136:139], v[92:95], v[190:193], v[136:139]
	v_mfma_f32_16x16x32_bf16 v[44:47], v[108:111], v[190:193], v[44:47]
	v_mfma_f32_16x16x32_bf16 v[128:131], v[92:95], v[198:201], v[128:131]
	v_mfma_f32_16x16x32_bf16 v[40:43], v[108:111], v[198:201], v[40:43]
	s_barrier
	ds_read_b128 v[202:205], v237 offset:49152
	ds_read_b128 v[206:209], v237 offset:50176
	s_add_i32 m0, s53, 0x18000
	ds_read_b128 v[210:213], v237 offset:51200
	global_load_lds_dwordx4 v168, s[98:99]
	s_add_i32 m0, s53, 0x1a000
	ds_read_b128 v[214:217], v237 offset:52224
	global_load_lds_dwordx4 v184, s[98:99]
	s_barrier
	s_waitcnt lgkmcnt(0)
	v_mfma_f32_16x16x32_bf16 v[140:143], v[202:205], v[124:127], v[144:147]
	v_mfma_f32_16x16x32_bf16 v[112:115], v[202:205], v[156:159], v[112:115]
	v_mfma_f32_16x16x32_bf16 v[144:147], v[206:209], v[132:135], v[140:143]
	v_mfma_f32_16x16x32_bf16 v[60:63], v[210:213], v[124:127], v[60:63]
	v_mfma_f32_16x16x32_bf16 v[140:143], v[206:209], v[160:163], v[112:115]
	v_mfma_f32_16x16x32_bf16 v[112:115], v[202:205], v[164:167], v[116:119]
	v_mfma_f32_16x16x32_bf16 v[60:63], v[214:217], v[132:135], v[60:63]
	v_mfma_f32_16x16x32_bf16 v[56:59], v[210:213], v[156:159], v[56:59]
	v_mfma_f32_16x16x32_bf16 v[132:135], v[206:209], v[190:193], v[112:115]
	v_mfma_f32_16x16x32_bf16 v[36:39], v[210:213], v[164:167], v[36:39]
	v_mfma_f32_16x16x32_bf16 v[112:115], v[202:205], v[194:197], v[120:123]
	v_mfma_f32_16x16x32_bf16 v[32:35], v[210:213], v[194:197], v[32:35]
	v_mfma_f32_16x16x32_bf16 v[56:59], v[214:217], v[160:163], v[56:59]
	v_mfma_f32_16x16x32_bf16 v[36:39], v[214:217], v[190:193], v[36:39]
	v_mfma_f32_16x16x32_bf16 v[124:127], v[206:209], v[198:201], v[112:115]
	v_mfma_f32_16x16x32_bf16 v[32:35], v[214:217], v[198:201], v[32:35]
	s_mov_b32 m0, s62
	s_barrier
	global_load_lds_dwordx4 v180, s[100:101]
	s_mov_b32 m0, s63
	s_nop 0
	global_load_lds_dwordx4 v182, s[100:101]
	s_barrier
	s_waitcnt lgkmcnt(0)
	s_barrier
	s_add_i32 m0, s53, 0x1c000
	s_add_u32 s2, s2, 0x40080
	s_addc_u32 s3, s3, 0
	global_load_lds_dwordx4 v168, s[2:3]
	s_add_i32 m0, s53, 0x1e000
	s_add_i32 s67, s67, 2
	global_load_lds_dwordx4 v184, s[2:3]
	s_waitcnt vmcnt(6)
	s_barrier
	s_add_u32 s10, s10, 0x100
	s_addc_u32 s11, s11, 0
	s_add_u32 s37, s37, 0x100
	s_addc_u32 s39, s39, 0
	s_cmp_gt_u32 s67, 13
	s_barrier
.Lup_half_loop:
	s_add_u32 s2, s10, 0xfffc0080
	s_addc_u32 s3, s11, -1
	ds_read_b128 v[48:51], v237
	ds_read_b128 v[52:55], v237 offset:1024
	ds_read_b128 v[104:107], v237 offset:2048
	ds_read_b128 v[108:111], v237 offset:3072
	s_cmp_eq_u32 s67, 12
	s_cselect_b32 s13, s1, s3
	s_cselect_b32 s12, s9, s2
	s_cselect_b32 s3, s14, s39
	s_cselect_b32 s2, s15, s37
	ds_read_b128 v[112:115], v238
	ds_read_b128 v[116:119], v238 offset:1024
	ds_read_b128 v[120:123], v238 offset:2048
	ds_read_b128 v[156:159], v238 offset:3072
	ds_read_b128 v[160:163], v238 offset:4096
	ds_read_b128 v[164:167], v238 offset:5120
	ds_read_b128 v[190:193], v238 offset:6144
	ds_read_b128 v[194:197], v238 offset:7168
	s_waitcnt lgkmcnt(8)
	s_barrier
	s_waitcnt lgkmcnt(0)
	v_mfma_f32_16x16x32_bf16 v[152:155], v[48:51], v[112:115], v[152:155]
	v_mfma_f32_16x16x32_bf16 v[68:71], v[104:107], v[112:115], v[68:71]
	v_mfma_f32_16x16x32_bf16 v[148:151], v[48:51], v[120:123], v[148:151]
	v_mfma_f32_16x16x32_bf16 v[64:67], v[104:107], v[120:123], v[64:67]
	v_mfma_f32_16x16x32_bf16 v[136:139], v[48:51], v[160:163], v[136:139]
	v_mfma_f32_16x16x32_bf16 v[44:47], v[104:107], v[160:163], v[44:47]
	v_mfma_f32_16x16x32_bf16 v[128:131], v[48:51], v[190:193], v[128:131]
	v_mfma_f32_16x16x32_bf16 v[40:43], v[104:107], v[190:193], v[40:43]
	v_mfma_f32_16x16x32_bf16 v[152:155], v[52:55], v[116:119], v[152:155]
	v_mfma_f32_16x16x32_bf16 v[68:71], v[108:111], v[116:119], v[68:71]
	v_mfma_f32_16x16x32_bf16 v[148:151], v[52:55], v[156:159], v[148:151]
	v_mfma_f32_16x16x32_bf16 v[64:67], v[108:111], v[156:159], v[64:67]
	v_mfma_f32_16x16x32_bf16 v[136:139], v[52:55], v[164:167], v[136:139]
	v_mfma_f32_16x16x32_bf16 v[44:47], v[108:111], v[164:167], v[44:47]
	v_mfma_f32_16x16x32_bf16 v[128:131], v[52:55], v[194:197], v[128:131]
	v_mfma_f32_16x16x32_bf16 v[40:43], v[108:111], v[194:197], v[40:43]
	s_barrier
	s_add_u32 s98, s2, 0x80
	s_addc_u32 s99, s3, 0
	s_add_i32 m0, s53, 0x10000
	ds_read_b128 v[198:201], v237 offset:16384
	ds_read_b128 v[202:205], v237 offset:17408
	ds_read_b128 v[206:209], v237 offset:18432
	global_load_lds_dwordx4 v168, s[2:3]
	s_add_i32 m0, s53, 0x12000
	ds_read_b128 v[210:213], v237 offset:19456
	global_load_lds_dwordx4 v184, s[2:3]
	s_barrier
	s_waitcnt lgkmcnt(0)
	v_mfma_f32_16x16x32_bf16 v[144:147], v[198:201], v[112:115], v[144:147]
	v_mfma_f32_16x16x32_bf16 v[60:63], v[206:209], v[112:115], v[60:63]
	v_mfma_f32_16x16x32_bf16 v[56:59], v[206:209], v[120:123], v[56:59]
	v_mfma_f32_16x16x32_bf16 v[36:39], v[206:209], v[160:163], v[36:39]
	v_mfma_f32_16x16x32_bf16 v[32:35], v[206:209], v[190:193], v[32:35]
	v_mfma_f32_16x16x32_bf16 v[144:147], v[202:205], v[116:119], v[144:147]
	v_mfma_f32_16x16x32_bf16 v[60:63], v[210:213], v[116:119], v[60:63]
	v_mfma_f32_16x16x32_bf16 v[112:115], v[198:201], v[120:123], v[140:143]
	v_mfma_f32_16x16x32_bf16 v[56:59], v[210:213], v[156:159], v[56:59]
	v_mfma_f32_16x16x32_bf16 v[116:119], v[198:201], v[160:163], v[132:135]
	v_mfma_f32_16x16x32_bf16 v[36:39], v[210:213], v[164:167], v[36:39]
	v_mfma_f32_16x16x32_bf16 v[120:123], v[198:201], v[190:193], v[124:127]
	v_mfma_f32_16x16x32_bf16 v[32:35], v[210:213], v[194:197], v[32:35]
	v_mfma_f32_16x16x32_bf16 v[112:115], v[202:205], v[156:159], v[112:115]
	v_mfma_f32_16x16x32_bf16 v[116:119], v[202:205], v[164:167], v[116:119]
	v_mfma_f32_16x16x32_bf16 v[120:123], v[202:205], v[194:197], v[120:123]
	s_mov_b32 m0, s54
	s_add_u32 s100, s12, 0x80
	s_addc_u32 s101, s13, 0
	s_barrier
	global_load_lds_dwordx4 v180, s[12:13]
	s_mov_b32 m0, s55
	s_nop 0
	global_load_lds_dwordx4 v182, s[12:13]
	s_barrier
	s_waitcnt lgkmcnt(0)
	s_barrier
	s_add_i32 m0, s53, 0x14000
	s_add_u32 s68, s2, 0x40000
	s_addc_u32 s69, s3, 0
	global_load_lds_dwordx4 v168, s[68:69]
	s_add_i32 m0, s53, 0x16000
	s_add_u32 s12, s12, 0x40000
	s_addc_u32 s13, s13, 0
	global_load_lds_dwordx4 v184, s[68:69]
	s_waitcnt vmcnt(6)
	s_barrier
	s_barrier
	ds_read_b128 v[76:79], v237 offset:32768
	ds_read_b128 v[92:95], v237 offset:33792
	ds_read_b128 v[104:107], v237 offset:34816
	ds_read_b128 v[108:111], v237 offset:35840
	ds_read_b128 v[124:127], v238 offset:32768
	ds_read_b128 v[132:135], v238 offset:33792
	ds_read_b128 v[156:159], v238 offset:34816
	ds_read_b128 v[160:163], v238 offset:35840
	ds_read_b128 v[164:167], v238 offset:36864
	ds_read_b128 v[190:193], v238 offset:37888
	ds_read_b128 v[194:197], v238 offset:38912
	ds_read_b128 v[198:201], v238 offset:39936
	s_waitcnt lgkmcnt(8)
	s_barrier
	s_waitcnt lgkmcnt(0)
	v_mfma_f32_16x16x32_bf16 v[140:143], v[76:79], v[124:127], v[152:155]
	v_mfma_f32_16x16x32_bf16 v[152:155], v[92:95], v[132:135], v[140:143]
	v_mfma_f32_16x16x32_bf16 v[68:71], v[104:107], v[124:127], v[68:71]
	v_mfma_f32_16x16x32_bf16 v[140:143], v[76:79], v[156:159], v[148:151]
	v_mfma_f32_16x16x32_bf16 v[64:67], v[104:107], v[156:159], v[64:67]
	v_mfma_f32_16x16x32_bf16 v[136:139], v[76:79], v[164:167], v[136:139]
	v_mfma_f32_16x16x32_bf16 v[44:47], v[104:107], v[164:167], v[44:47]
	v_mfma_f32_16x16x32_bf16 v[128:131], v[76:79], v[194:197], v[128:131]
	v_mfma_f32_16x16x32_bf16 v[40:43], v[104:107], v[194:197], v[40:43]
	v_mfma_f32_16x16x32_bf16 v[68:71], v[108:111], v[132:135], v[68:71]
	v_mfma_f32_16x16x32_bf16 v[148:151], v[92:95], v[160:163], v[140:143]
	v_mfma_f32_16x16x32_bf16 v[64:67], v[108:111], v[160:163], v[64:67]
	v_mfma_f32_16x16x32_bf16 v[136:139], v[92:95], v[190:193], v[136:139]
	v_mfma_f32_16x16x32_bf16 v[44:47], v[108:111], v[190:193], v[44:47]
	v_mfma_f32_16x16x32_bf16 v[128:131], v[92:95], v[198:201], v[128:131]
	v_mfma_f32_16x16x32_bf16 v[40:43], v[108:111], v[198:201], v[40:43]
	s_barrier
	ds_read_b128 v[202:205], v237 offset:49152
	ds_read_b128 v[206:209], v237 offset:50176
	s_add_i32 m0, s53, 0x18000
	ds_read_b128 v[210:213], v237 offset:51200
	global_load_lds_dwordx4 v168, s[98:99]
	s_add_i32 m0, s53, 0x1a000
	ds_read_b128 v[214:217], v237 offset:52224
	global_load_lds_dwordx4 v184, s[98:99]
	s_barrier
	s_waitcnt lgkmcnt(0)
	v_mfma_f32_16x16x32_bf16 v[140:143], v[202:205], v[124:127], v[144:147]
	v_mfma_f32_16x16x32_bf16 v[112:115], v[202:205], v[156:159], v[112:115]
	v_mfma_f32_16x16x32_bf16 v[144:147], v[206:209], v[132:135], v[140:143]
	v_mfma_f32_16x16x32_bf16 v[60:63], v[210:213], v[124:127], v[60:63]
	v_mfma_f32_16x16x32_bf16 v[140:143], v[206:209], v[160:163], v[112:115]
	v_mfma_f32_16x16x32_bf16 v[112:115], v[202:205], v[164:167], v[116:119]
	v_mfma_f32_16x16x32_bf16 v[60:63], v[214:217], v[132:135], v[60:63]
	v_mfma_f32_16x16x32_bf16 v[56:59], v[210:213], v[156:159], v[56:59]
	v_mfma_f32_16x16x32_bf16 v[132:135], v[206:209], v[190:193], v[112:115]
	v_mfma_f32_16x16x32_bf16 v[36:39], v[210:213], v[164:167], v[36:39]
	v_mfma_f32_16x16x32_bf16 v[112:115], v[202:205], v[194:197], v[120:123]
	v_mfma_f32_16x16x32_bf16 v[32:35], v[210:213], v[194:197], v[32:35]
	v_mfma_f32_16x16x32_bf16 v[56:59], v[214:217], v[160:163], v[56:59]
	v_mfma_f32_16x16x32_bf16 v[36:39], v[214:217], v[190:193], v[36:39]
	v_mfma_f32_16x16x32_bf16 v[124:127], v[206:209], v[198:201], v[112:115]
	v_mfma_f32_16x16x32_bf16 v[32:35], v[214:217], v[198:201], v[32:35]
	s_mov_b32 m0, s62
	s_barrier
	global_load_lds_dwordx4 v180, s[100:101]
	s_mov_b32 m0, s63
	s_nop 0
	global_load_lds_dwordx4 v182, s[100:101]
	s_barrier
	s_waitcnt lgkmcnt(0)
	s_barrier
	s_add_i32 m0, s53, 0x1c000
	s_add_u32 s2, s2, 0x40080
	s_addc_u32 s3, s3, 0
	global_load_lds_dwordx4 v168, s[2:3]
	s_add_i32 m0, s53, 0x1e000
	s_add_i32 s67, s67, 2
	global_load_lds_dwordx4 v184, s[2:3]
	s_waitcnt vmcnt(6)
	s_barrier
	s_add_u32 s10, s10, 0x100
	s_addc_u32 s11, s11, 0
	s_add_u32 s37, s37, 0x100
	s_addc_u32 s39, s39, 0
	s_cmp_gt_u32 s67, 13
	s_barrier
	s_cbranch_scc0 .Lup_half_loop
	s_branch .Lup_epi
